# phase 0a cast_rows loop software-pipelined (next row prefetched; counted wait leaves the stores outstanding)
# baseline (speedup 1.0000x reference)
; __device__ __forceinline__ unsigned cvtpk(float lo, float hi) { f32x2_t v = {lo, hi}; bf16x2_t b = __builtin_convertvector(v, bf16x2_t); return __builtin_bit_cast(unsigned, b); }
; __device__ __forceinline__ void cast_rows(const float* X, bf16_t* XB, float* ssp, int nrows, int gw, int NGW, int lane) {
;     for (int m = gw; m < nrows; m += NGW) { const f32x4* xr = (const f32x4*)(X + (size_t)m * DM) + lane;
;         f32x4 v[4]; float s = 0.f;
; #pragma unroll
;         for (int j = 0; j < 4; ++j) { v[j] = xr[64 * j]; s += (v[j].x * v[j].x + v[j].y * v[j].y) + (v[j].z * v[j].z + v[j].w * v[j].w); }
;         s = wave_sum(s);
;         u32x2v* o8 = (u32x2v*)(XB + (size_t)m * DM) + lane;
; #pragma unroll
;         for (int j = 0; j < 4; ++j) { u32x2v w; w.x = cvtpk(v[j].x, v[j].y); w.y = cvtpk(v[j].z, v[j].w); o8[64 * j] = w; }
;         if (lane < 16) ssp[(size_t)m * 16 + lane] = lane == 0 ? s : 0.f; }
; }
.LBB0_210:
	s_or_b64 exec, exec, s[12:13]
	s_add_i32 s3, s3, s76
	v_lshl_add_u64 v[6:7], v[6:7], 0, s[0:1]
	v_lshl_add_u64 v[4:5], v[4:5], 0, s[6:7]
	s_cmp_lt_i32 s3, 0x10000
	s_cbranch_scc0 .LBB0_213
	s_waitcnt vmcnt(5)
	v_mov_b32_e32 v14, v78
	v_mov_b32_e32 v15, v79
	v_mov_b32_e32 v16, v80
	v_mov_b32_e32 v17, v81
	v_mov_b32_e32 v18, v82
	v_mov_b32_e32 v19, v83
	v_mov_b32_e32 v20, v84
	v_mov_b32_e32 v21, v85
	v_mov_b32_e32 v22, v86
	v_mov_b32_e32 v23, v87
	v_mov_b32_e32 v24, v88
	v_mov_b32_e32 v25, v89
	v_mov_b32_e32 v26, v90
	v_mov_b32_e32 v27, v91
	v_mov_b32_e32 v28, v92
	v_mov_b32_e32 v29, v93
	s_branch .Lcast_body
.LBB0_211:
	s_waitcnt lgkmcnt(0)
	global_load_dwordx4 v[14:17], v[2:3], off offset:-3072
	global_load_dwordx4 v[18:21], v[2:3], off offset:-2048
	global_load_dwordx4 v[22:25], v[2:3], off offset:-1024
	global_load_dwordx4 v[26:29], v[2:3], off
	v_lshl_add_u64 v[2:3], v[2:3], 0, s[10:11]
	s_waitcnt vmcnt(0)
.Lcast_body:
	s_add_i32 s12, s3, s76
	s_cmp_lt_i32 s12, 0x10000
	s_cbranch_scc0 .Lcast_nopf
	global_load_dwordx4 v[78:81], v[2:3], off offset:-3072
	global_load_dwordx4 v[82:85], v[2:3], off offset:-2048
	global_load_dwordx4 v[86:89], v[2:3], off offset:-1024
	global_load_dwordx4 v[90:93], v[2:3], off
	v_lshl_add_u64 v[2:3], v[2:3], 0, s[10:11]
.Lcast_nopf:
	v_mul_f32_e32 v1, v15, v15
	v_mul_f32_e32 v30, v17, v17
	v_mul_f32_e32 v31, v19, v19
	v_mul_f32_e32 v32, v21, v21
	v_mul_f32_e32 v33, v23, v23
	v_mul_f32_e32 v34, v25, v25
	v_fmac_f32_e32 v1, v14, v14
	v_fmac_f32_e32 v30, v16, v16
	v_fmac_f32_e32 v31, v18, v18
	v_fmac_f32_e32 v32, v20, v20
	v_mul_f32_e32 v35, v27, v27
	v_mul_f32_e32 v36, v29, v29
	v_fmac_f32_e32 v33, v22, v22
	v_fmac_f32_e32 v34, v24, v24
	v_add_f32_e32 v1, v1, v30
	v_add_f32_e32 v30, v31, v32
	v_fmac_f32_e32 v35, v26, v26
	v_fmac_f32_e32 v36, v28, v28
	v_add_f32_e32 v31, v33, v34
	v_add_f32_e32 v1, v1, v30
	v_add_f32_e32 v32, v35, v36
	v_add_f32_e32 v1, v1, v31
	v_add_f32_e32 v1, v1, v32
	ds_bpermute_b32 v30, v8, v1
	v_cvt_pk_bf16_f32 v14, v14, v15
	v_cvt_pk_bf16_f32 v15, v16, v17
	v_cvt_pk_bf16_f32 v16, v18, v19
	v_cvt_pk_bf16_f32 v17, v20, v21
	s_waitcnt lgkmcnt(0)
	v_add_f32_e32 v1, v1, v30
	ds_bpermute_b32 v30, v9, v1
	global_store_dwordx2 v[4:5], v[14:15], off offset:-1024
	global_store_dwordx2 v[4:5], v[16:17], off offset:-512
	v_cvt_pk_bf16_f32 v18, v22, v23
	v_cvt_pk_bf16_f32 v16, v26, v27
	v_cvt_pk_bf16_f32 v17, v28, v29
	s_waitcnt lgkmcnt(0)
	v_add_f32_e32 v1, v1, v30
	ds_bpermute_b32 v30, v10, v1
	global_store_dwordx2 v[4:5], v[16:17], off offset:512
	s_waitcnt lgkmcnt(0)
	v_add_f32_e32 v1, v1, v30
	ds_bpermute_b32 v30, v11, v1
	s_waitcnt lgkmcnt(0)
	v_add_f32_e32 v1, v1, v30
	ds_bpermute_b32 v19, v12, v1
	s_waitcnt lgkmcnt(0)
	v_add_f32_e32 v1, v1, v19
	ds_bpermute_b32 v14, v13, v1
	v_cvt_pk_bf16_f32 v19, v24, v25
	global_store_dwordx2 v[4:5], v[18:19], off
	s_and_saveexec_b64 s[12:13], vcc
	s_cbranch_execz .LBB0_210
	s_waitcnt lgkmcnt(0)
	v_add_f32_e32 v1, v1, v14
	v_cndmask_b32_e64 v1, 0, v1, s[4:5]
	global_store_dword v[6:7], v1, off
	s_branch .LBB0_210
